# grid barrier: non-leaders poll the top-level generation word directly (one hop less)
# speedup vs baseline: 1.0140x; 1.0140x over previous
; __device__ __forceinline__ unsigned xb_ld(unsigned* p)              { return __hip_atomic_load(p, __ATOMIC_RELAXED, __HIP_MEMORY_SCOPE_AGENT); }
; __device__ __forceinline__ unsigned xb_add(unsigned* p, unsigned v) { return __hip_atomic_fetch_add(p, v, __ATOMIC_RELAXED, __HIP_MEMORY_SCOPE_AGENT); }
; #define XB_SPIN(cond, bar) do { unsigned _sp = 0; while (cond) { __builtin_amdgcn_s_sleep(1); \
;     if ((++_sp & 255u) == 0u) { if (xb_ld(&(bar)[XB_TMO])) break; if (_sp > XB_SPIN_CAP) { atomicAdd(&(bar)[XB_TMO], 1u); break; } } } } while (0)
; __device__ __forceinline__ void xcd_barrier(const XcdBarrier& b) {
;     ...
;         const unsigned old = xb_add(&bar[XB_XSUB(b.x)], 1u);
;         const unsigned gen = old / nloc;
;         if (old + 1u == (gen + 1u) * nloc) {
;             __builtin_amdgcn_fence(__ATOMIC_RELEASE, "agent");
;             asm volatile("s_waitcnt vmcnt(0)" ::: "memory");
;             const unsigned og = xb_add(&bar[XB_TOP], 1u);
;             const unsigned tg = og / nx;
;             if (og + 1u == (tg + 1u) * nx) xb_add(&bar[XB_TOPGEN], 1u);
;             else XB_SPIN(xb_ld(&bar[XB_TOPGEN]) == tg, bar);
;             __builtin_amdgcn_fence(__ATOMIC_ACQUIRE, "agent");
;             xb_add(&bar[XB_XGEN(b.x)], 1u);
;             asm volatile("s_waitcnt vmcnt(0)" ::: "memory");
;         } else {
;             XB_SPIN(xb_ld(&bar[XB_XGEN(b.x)]) == gen, bar);
;             __builtin_amdgcn_fence(__ATOMIC_ACQUIRE, "agent");
;             asm volatile("s_waitcnt vmcnt(0)" ::: "memory");
;         }
.LBB0_117:
	s_or_b64 exec, exec, s[12:13]
	v_cvt_f32_u32_e32 v4, v2
	s_waitcnt vmcnt(0)
	v_readfirstlane_b32 s3, v3
	v_sub_u32_e32 v3, 0, v2
	v_rcp_iflag_f32_e32 v4, v4
	v_add_u32_e32 v5, s3, v1
	v_mul_f32_e32 v4, 0x4f7ffffe, v4
	v_cvt_u32_f32_e32 v4, v4
	v_mul_lo_u32 v1, v3, v4
	v_mul_hi_u32 v1, v4, v1
	v_add_u32_e32 v1, v4, v1
	v_mul_hi_u32 v1, v5, v1
	v_mul_lo_u32 v3, v1, v2
	v_sub_u32_e32 v3, v5, v3
	v_add_u32_e32 v4, 1, v1
	v_cmp_ge_u32_e32 vcc, v3, v2
	s_nop 1
	v_cndmask_b32_e32 v1, v1, v4, vcc
	v_sub_u32_e32 v4, v3, v2
	v_cndmask_b32_e32 v3, v3, v4, vcc
	v_add_u32_e32 v4, 1, v1
	v_cmp_ge_u32_e32 vcc, v3, v2
	v_add_u32_e32 v3, 1, v5
	s_nop 0
	v_cndmask_b32_e32 v1, v1, v4, vcc
	v_mul_lo_u32 v4, v2, v1
	v_add_u32_e32 v2, v4, v2
	v_cmp_ne_u32_e32 vcc, v3, v2
	s_and_saveexec_b64 s[10:11], vcc
	s_xor_b64 s[10:11], exec, s[10:11]
	s_cbranch_execz .LBB0_131
	s_waitcnt lgkmcnt(0)
	v_mov_b32_e32 v0, 0x1ba7c100
	global_load_dword v0, v0, s[84:85] offset:1024 sc1
	s_add_u32 s16, s84, 0x1ba7c500
	s_addc_u32 s17, s85, 0
	s_waitcnt vmcnt(0)
	v_cmp_eq_u32_e32 vcc, v0, v1
	s_and_saveexec_b64 s[12:13], vcc
	s_cbranch_execz .LBB0_130
	s_add_u32 s14, s84, 0x1ba79200
	s_addc_u32 s15, s85, 0
	s_mov_b32 s3, 1
	s_mov_b64 s[18:19], 0
	v_mov_b32_e32 v0, 0
	s_branch .LBB0_121

; __device__ __forceinline__ unsigned xb_ld(unsigned* p)              { return __hip_atomic_load(p, __ATOMIC_RELAXED, __HIP_MEMORY_SCOPE_AGENT); }
; __device__ __forceinline__ unsigned xb_add(unsigned* p, unsigned v) { return __hip_atomic_fetch_add(p, v, __ATOMIC_RELAXED, __HIP_MEMORY_SCOPE_AGENT); }
; #define XB_SPIN(cond, bar) do { unsigned _sp = 0; while (cond) { __builtin_amdgcn_s_sleep(1); \
;     if ((++_sp & 255u) == 0u) { if (xb_ld(&(bar)[XB_TMO])) break; if (_sp > XB_SPIN_CAP) { atomicAdd(&(bar)[XB_TMO], 1u); break; } } } } while (0)
; __device__ __forceinline__ void xcd_barrier(const XcdBarrier& b) {
;     ...
;         const unsigned old = xb_add(&bar[XB_XSUB(b.x)], 1u);
;         const unsigned gen = old / nloc;
;         if (old + 1u == (gen + 1u) * nloc) {
;             __builtin_amdgcn_fence(__ATOMIC_RELEASE, "agent");
;             asm volatile("s_waitcnt vmcnt(0)" ::: "memory");
;             const unsigned og = xb_add(&bar[XB_TOP], 1u);
;             const unsigned tg = og / nx;
;             if (og + 1u == (tg + 1u) * nx) xb_add(&bar[XB_TOPGEN], 1u);
;             else XB_SPIN(xb_ld(&bar[XB_TOPGEN]) == tg, bar);
;             __builtin_amdgcn_fence(__ATOMIC_ACQUIRE, "agent");
;             xb_add(&bar[XB_XGEN(b.x)], 1u);
;             asm volatile("s_waitcnt vmcnt(0)" ::: "memory");
;         } else {
;             XB_SPIN(xb_ld(&bar[XB_XGEN(b.x)]) == gen, bar);
;             __builtin_amdgcn_fence(__ATOMIC_ACQUIRE, "agent");
;             asm volatile("s_waitcnt vmcnt(0)" ::: "memory");
;         }
.LBB0_2058:
	s_or_b64 exec, exec, s[6:7]
	v_cvt_f32_u32_e32 v4, v2
	s_waitcnt vmcnt(0)
	v_readfirstlane_b32 s4, v3
	v_sub_u32_e32 v3, 0, v2
	v_rcp_iflag_f32_e32 v4, v4
	v_add_u32_e32 v5, s4, v1
	v_mul_f32_e32 v4, 0x4f7ffffe, v4
	v_cvt_u32_f32_e32 v4, v4
	v_mul_lo_u32 v1, v3, v4
	v_mul_hi_u32 v1, v4, v1
	v_add_u32_e32 v1, v4, v1
	v_mul_hi_u32 v1, v5, v1
	v_mul_lo_u32 v3, v1, v2
	v_sub_u32_e32 v3, v5, v3
	v_add_u32_e32 v4, 1, v1
	v_cmp_ge_u32_e32 vcc, v3, v2
	s_nop 1
	v_cndmask_b32_e32 v1, v1, v4, vcc
	v_sub_u32_e32 v4, v3, v2
	v_cndmask_b32_e32 v3, v3, v4, vcc
	v_add_u32_e32 v4, 1, v1
	v_cmp_ge_u32_e32 vcc, v3, v2
	v_add_u32_e32 v3, 1, v5
	s_nop 0
	v_cndmask_b32_e32 v1, v1, v4, vcc
	v_mul_lo_u32 v4, v2, v1
	v_add_u32_e32 v2, v4, v2
	v_cmp_ne_u32_e32 vcc, v3, v2
	s_and_saveexec_b64 s[4:5], vcc
	s_xor_b64 s[4:5], exec, s[4:5]
	s_cbranch_execz .LBB0_2072
	s_waitcnt lgkmcnt(0)
	v_mov_b32_e32 v0, 0x1ba7c100
	global_load_dword v0, v0, s[84:85] offset:1024 sc1
	s_add_u32 s10, s84, 0x1ba7c500
	s_addc_u32 s11, s85, 0
	s_waitcnt vmcnt(0)
	v_cmp_eq_u32_e32 vcc, v0, v1
	s_and_saveexec_b64 s[6:7], vcc
	s_cbranch_execz .LBB0_2071
	s_add_u32 s8, s84, 0x1ba79200
	s_addc_u32 s9, s85, 0
	s_mov_b32 s22, 1
	s_mov_b64 s[12:13], 0
	v_mov_b32_e32 v0, 0
	s_branch .LBB0_2062
